# even in-proj RoPE epilogue rewritten by hand: cos/sin loads batched two steps ahead, stores no longer serialize the loads
# baseline (speedup 1.0000x reference)
; DI u32x2 pack4(float a, float b, float c, float d) { u32x2 w; w.x = pack2(a, b); w.y = pack2(c, d); return w; }
;   DI void rope(const f32x16 (&acc)[4][2], int row0, int r, int h, const float* sR, bf16_t* dst, int H, int hh, float scale, bf16_t* st) const {
;     const int lane = h * 32 + r, b = row0 >> 12, sb = row0 & 4095;
; #pragma unroll
;     for (int mi = 0; mi < 4; ++mi) {
;       const int s = sb + mi * 32 + r;
;       const float rv = sR[mi * 32 + r] * scale;
; #pragma unroll
;       for (int g = 0; g < 4; ++g) {
;         const int d0 = 8 * g + 4 * h;
;         const f32x4 c = *(const f32x4*)(cosT + s * 32 + d0), sn = *(const f32x4*)(sinT + s * 32 + d0);
;         float o1[4], o2[4];
; #pragma unroll
;         for (int q = 0; q < 4; ++q) {
;           const float x1 = acc[mi][0][4 * g + q] * rv, x2 = acc[mi][1][4 * g + q] * rv;
;           o1[q] = x1 * c[q] - x2 * sn[q]; o2[q] = x1 * sn[q] + x2 * c[q];
;         }
;         *(u32x2*)(st + r * 72 + d0) = pack4(o1[0], o1[1], o1[2], o1[3]);
;         *(u32x2*)(st + r * 72 + 32 + d0) = pack4(o2[0], o2[1], o2[2], o2[3]);
;       }
;       flush_rows(st, dst + ((size_t)(b * H + hh) * S + sb + mi * 32) * 64, lane);
;     }
;   }
;   DI void operator()(const f32x16 (&acc)[4][2], bool vt, int row0, int col0, int r, int h, const float* sR, float* stage) const {
;     const int seg = col0 >> 6;
;     bf16_t* st = (bf16_t*)stage;
;     if (seg < 8) rope(acc, row0, r, h, sR, eb.QN, 8, seg, 0.125f, st);
;     else if (seg < 10) rope(acc, row0, r, h, sR, eb.KC, 2, seg - 8, 1.f, st);
;     else if (seg < 12) rowmajor(acc, row0, r, h, sR, eb.VC, 2, seg - 10, 1.f, st);
;     else if (seg < 14) rope(acc, row0, r, h, sR, eb.KS, 2, seg - 12, 1.f, st);
;     else if (seg < 16) transposed(acc, row0, r, h, sR, eb.VST, 2, seg - 14, st);
;     else if (seg < 18) rope(acc, row0, r, h, sR, eb.KW, 2, seg - 16, 1.f, st);
;     else if (seg < 20) transposed(acc, row0, r, h, sR, eb.VWT, 2, seg - 18, st);
;     else if (seg < 28) rope(acc, row0, r, h, sR, eb.DQ, 8, seg - 20, 0.125f, st);
;     else if (seg < 36) rope(acc, row0, r, h, sR, eb.DK, 8, seg - 28, 1.f, st);
;     else if (seg < 44) transposed(acc, row0, r, h, sR, eb.DVT, 8, seg - 36, st);
.LBB0_659:
	s_lshl_b32 s36, s49, 7
	v_lshl_or_b32 v32, v156, 6, s36
	v_mul_lo_u32 v130, v155, s75
	v_add_u32_e32 v134, s55, v130
	v_and_b32_e32 v130, 0xffffff80, v154
	v_ashrrev_i32_e32 v132, 6, v32
	v_add_u32_e32 v133, s33, v130
	v_lshl_add_u32 v136, v130, 2, v210
	v_cmp_lt_i32_e32 vcc, 7, v132
	s_waitcnt vmcnt(0) lgkmcnt(0)
	s_barrier
	v_readfirstlane_b32 s36, v132
	s_mov_b32 s42, 1.0
	s_mov_b32 s40, 1
	s_cmp_lt_u32 s36, 8
	s_cbranch_scc0 .Lrp_1
	s_mov_b64 s[38:39], s[2:3]
	s_mov_b32 s40, 3
	s_mov_b32 s41, s36
	s_mov_b32 s42, 0x3e000000
	s_branch .Lrp_go
.Lrp_1:
	s_cmp_lt_u32 s36, 10
	s_cbranch_scc0 .Lrp_2
	s_mov_b64 s[38:39], s[8:9]
	s_sub_u32 s41, s36, 8
	s_branch .Lrp_go
.Lrp_2:
	s_cmp_lt_u32 s36, 12
	s_cbranch_scc1 .Lrope_skip
	s_cmp_lt_u32 s36, 14
	s_cbranch_scc0 .Lrp_3
	s_mov_b64 s[38:39], s[12:13]
	s_sub_u32 s41, s36, 12
	s_branch .Lrp_go
.Lrp_3:
	s_cmp_lt_u32 s36, 16
	s_cbranch_scc1 .Lrope_skip
	s_cmp_lt_u32 s36, 18
	s_cbranch_scc0 .Lrp_4
	s_mov_b64 s[38:39], s[16:17]
	s_sub_u32 s41, s36, 16
	s_branch .Lrp_go
.Lrp_4:
	s_cmp_lt_u32 s36, 20
	s_cbranch_scc1 .Lrope_skip
	s_cmp_lt_u32 s36, 28
	s_cbranch_scc0 .Lrp_5
	s_mov_b64 s[38:39], s[20:21]
	s_mov_b32 s40, 3
	s_sub_u32 s41, s36, 20
	s_mov_b32 s42, 0x3e000000
	s_branch .Lrp_go
.Lrp_5:
	s_cmp_lt_u32 s36, 36
	s_cbranch_scc0 .Lrope_skip
	s_mov_b64 s[38:39], s[22:23]
	s_mov_b32 s40, 3
	s_sub_u32 s41, s36, 28
.Lrp_go:
	v_and_b32_e32 v156, 31, v242
	v_bfe_u32 v157, v242, 5, 1
	v_bfe_u32 v158, v242, 3, 3
	v_and_b32_e32 v137, 7, v242
	v_and_b32_e32 v138, 0xfff, v133
	v_lshrrev_b32_e32 v139, 12, v133
	v_mul_u32_u24_e32 v135, 0x90, v158
	v_lshl_add_u32 v135, v137, 4, v135
	v_add_u32_e32 v135, v134, v135
	v_mul_u32_u24_e32 v130, 0x90, v156
	v_lshl_add_u32 v130, v157, 3, v130
	v_add_u32_e32 v134, v134, v130
	v_lshl_add_u32 v136, v156, 2, v136
	v_add_u32_e32 v132, v138, v156
	v_lshlrev_b32_e32 v132, 7, v132
	v_lshl_add_u32 v132, v157, 4, v132
	v_lshlrev_b32_e32 v139, s40, v139
	v_add_u32_e32 v139, s41, v139
	v_lshl_add_u32 v139, v139, 12, v138
	v_add_u32_e32 v139, v139, v158
	v_lshlrev_b32_e32 v139, 7, v139
	v_lshl_add_u32 v137, v137, 4, v139
	global_load_dwordx4 v[140:143], v132, s[4:5]
	global_load_dwordx4 v[144:147], v132, s[6:7]
	global_load_dwordx4 v[148:151], v132, s[4:5] offset:32
	global_load_dwordx4 v[152:155], v132, s[6:7] offset:32
	ds_read_b32 v32, v136
	s_waitcnt lgkmcnt(0)
	v_mul_f32_e32 v32, s42, v32
	s_waitcnt vmcnt(0)
	v_pk_mul_f32 v[98:99], v[98:99], v[32:33] op_sel_hi:[1,0]
	v_pk_mul_f32 v[100:101], v[100:101], v[32:33] op_sel_hi:[1,0]
	v_pk_mul_f32 v[114:115], v[114:115], v[32:33] op_sel_hi:[1,0]
	v_pk_mul_f32 v[116:117], v[116:117], v[32:33] op_sel_hi:[1,0]
	v_pk_mul_f32 v[130:131], v[98:99], v[144:145]
	v_pk_mul_f32 v[138:139], v[100:101], v[146:147]
	v_pk_mul_f32 v[144:145], v[114:115], v[144:145]
	v_pk_mul_f32 v[146:147], v[116:117], v[146:147]
	v_pk_fma_f32 v[98:99], v[98:99], v[140:141], v[144:145] neg_lo:[0,0,1] neg_hi:[0,0,1]
	v_pk_fma_f32 v[100:101], v[100:101], v[142:143], v[146:147] neg_lo:[0,0,1] neg_hi:[0,0,1]
	v_pk_fma_f32 v[114:115], v[114:115], v[140:141], v[130:131]
	v_pk_fma_f32 v[116:117], v[116:117], v[142:143], v[138:139]
	v_cvt_pk_bf16_f32 v130, v98, v99
	v_cvt_pk_bf16_f32 v131, v100, v101
	v_cvt_pk_bf16_f32 v138, v114, v115
	v_cvt_pk_bf16_f32 v139, v116, v117
	ds_write_b64 v134, v[130:131]
	ds_write_b64 v134, v[138:139] offset:64
	v_pk_mul_f32 v[102:103], v[102:103], v[32:33] op_sel_hi:[1,0]
	v_pk_mul_f32 v[104:105], v[104:105], v[32:33] op_sel_hi:[1,0]
	v_pk_mul_f32 v[118:119], v[118:119], v[32:33] op_sel_hi:[1,0]
	v_pk_mul_f32 v[120:121], v[120:121], v[32:33] op_sel_hi:[1,0]
	v_pk_mul_f32 v[130:131], v[102:103], v[152:153]
	v_pk_mul_f32 v[138:139], v[104:105], v[154:155]
	v_pk_mul_f32 v[152:153], v[118:119], v[152:153]
	v_pk_mul_f32 v[154:155], v[120:121], v[154:155]
	v_pk_fma_f32 v[102:103], v[102:103], v[148:149], v[152:153] neg_lo:[0,0,1] neg_hi:[0,0,1]
	v_pk_fma_f32 v[104:105], v[104:105], v[150:151], v[154:155] neg_lo:[0,0,1] neg_hi:[0,0,1]
	v_pk_fma_f32 v[118:119], v[118:119], v[148:149], v[130:131]
	v_pk_fma_f32 v[120:121], v[120:121], v[150:151], v[138:139]
	v_cvt_pk_bf16_f32 v130, v102, v103
	v_cvt_pk_bf16_f32 v131, v104, v105
	v_cvt_pk_bf16_f32 v138, v118, v119
	v_cvt_pk_bf16_f32 v139, v120, v121
	ds_write_b64 v134, v[130:131] offset:16
	ds_write_b64 v134, v[138:139] offset:80
	global_load_dwordx4 v[140:143], v132, s[4:5] offset:64
	global_load_dwordx4 v[144:147], v132, s[6:7] offset:64
	global_load_dwordx4 v[148:151], v132, s[4:5] offset:96
	global_load_dwordx4 v[152:155], v132, s[6:7] offset:96
	v_add_u32_e32 v132, 0x1000, v132
	global_load_dwordx4 v[98:101], v132, s[4:5]
	global_load_dwordx4 v[102:105], v132, s[6:7]
	global_load_dwordx4 v[114:117], v132, s[4:5] offset:32
	global_load_dwordx4 v[118:121], v132, s[6:7] offset:32
	s_waitcnt vmcnt(4)
; DI u32x2 pack4(float a, float b, float c, float d) { u32x2 w; w.x = pack2(a, b); w.y = pack2(c, d); return w; }
;   DI void rope(const f32x16 (&acc)[4][2], int row0, int r, int h, const float* sR, bf16_t* dst, int H, int hh, float scale, bf16_t* st) const {
;     ...
;     for (int mi = 0; mi < 4; ++mi) {
;       const int s = sb + mi * 32 + r;
;       const float rv = sR[mi * 32 + r] * scale;
; #pragma unroll
;       for (int g = 0; g < 4; ++g) {
;         const int d0 = 8 * g + 4 * h;
;         const f32x4 c = *(const f32x4*)(cosT + s * 32 + d0), sn = *(const f32x4*)(sinT + s * 32 + d0);
;         float o1[4], o2[4];
; #pragma unroll
;         for (int q = 0; q < 4; ++q) {
;           const float x1 = acc[mi][0][4 * g + q] * rv, x2 = acc[mi][1][4 * g + q] * rv;
;           o1[q] = x1 * c[q] - x2 * sn[q]; o2[q] = x1 * sn[q] + x2 * c[q];
;         }
;         *(u32x2*)(st + r * 72 + d0) = pack4(o1[0], o1[1], o1[2], o1[3]);
;         *(u32x2*)(st + r * 72 + 32 + d0) = pack4(o2[0], o2[1], o2[2], o2[3]);
;       }
;       flush_rows(st, dst + ((size_t)(b * H + hh) * S + sb + mi * 32) * 64, lane);
	v_pk_mul_f32 v[106:107], v[106:107], v[32:33] op_sel_hi:[1,0]
	v_pk_mul_f32 v[108:109], v[108:109], v[32:33] op_sel_hi:[1,0]
	v_pk_mul_f32 v[122:123], v[122:123], v[32:33] op_sel_hi:[1,0]
	v_pk_mul_f32 v[124:125], v[124:125], v[32:33] op_sel_hi:[1,0]
	v_pk_mul_f32 v[130:131], v[106:107], v[144:145]
	v_pk_mul_f32 v[138:139], v[108:109], v[146:147]
	v_pk_mul_f32 v[144:145], v[122:123], v[144:145]
	v_pk_mul_f32 v[146:147], v[124:125], v[146:147]
	v_pk_fma_f32 v[106:107], v[106:107], v[140:141], v[144:145] neg_lo:[0,0,1] neg_hi:[0,0,1]
	v_pk_fma_f32 v[108:109], v[108:109], v[142:143], v[146:147] neg_lo:[0,0,1] neg_hi:[0,0,1]
	v_pk_fma_f32 v[122:123], v[122:123], v[140:141], v[130:131]
	v_pk_fma_f32 v[124:125], v[124:125], v[142:143], v[138:139]
	v_cvt_pk_bf16_f32 v130, v106, v107
	v_cvt_pk_bf16_f32 v131, v108, v109
	v_cvt_pk_bf16_f32 v138, v122, v123
	v_cvt_pk_bf16_f32 v139, v124, v125
	ds_write_b64 v134, v[130:131] offset:32
	ds_write_b64 v134, v[138:139] offset:96
	v_pk_mul_f32 v[110:111], v[110:111], v[32:33] op_sel_hi:[1,0]
	v_pk_mul_f32 v[112:113], v[112:113], v[32:33] op_sel_hi:[1,0]
	v_pk_mul_f32 v[126:127], v[126:127], v[32:33] op_sel_hi:[1,0]
	v_pk_mul_f32 v[128:129], v[128:129], v[32:33] op_sel_hi:[1,0]
	v_pk_mul_f32 v[130:131], v[110:111], v[152:153]
	v_pk_mul_f32 v[138:139], v[112:113], v[154:155]
	v_pk_mul_f32 v[152:153], v[126:127], v[152:153]
	v_pk_mul_f32 v[154:155], v[128:129], v[154:155]
	v_pk_fma_f32 v[110:111], v[110:111], v[148:149], v[152:153] neg_lo:[0,0,1] neg_hi:[0,0,1]
	v_pk_fma_f32 v[112:113], v[112:113], v[150:151], v[154:155] neg_lo:[0,0,1] neg_hi:[0,0,1]
	v_pk_fma_f32 v[126:127], v[126:127], v[148:149], v[130:131]
	v_pk_fma_f32 v[128:129], v[128:129], v[150:151], v[138:139]
	v_cvt_pk_bf16_f32 v130, v110, v111
	v_cvt_pk_bf16_f32 v131, v112, v113
	v_cvt_pk_bf16_f32 v138, v126, v127
	v_cvt_pk_bf16_f32 v139, v128, v129
	ds_write_b64 v134, v[130:131] offset:48
	ds_write_b64 v134, v[138:139] offset:112
	global_load_dwordx4 v[140:143], v132, s[4:5] offset:64
	global_load_dwordx4 v[144:147], v132, s[6:7] offset:64
	global_load_dwordx4 v[148:151], v132, s[4:5] offset:96
	global_load_dwordx4 v[152:155], v132, s[6:7] offset:96
	ds_read_b128 v[106:109], v135
	ds_read_b128 v[110:113], v135 offset:1152
	ds_read_b128 v[122:125], v135 offset:2304
	ds_read_b128 v[126:129], v135 offset:3456
	s_waitcnt lgkmcnt(3)
	global_store_dwordx4 v137, v[106:109], s[38:39]
	s_waitcnt lgkmcnt(2)
	global_store_dwordx4 v137, v[110:113], s[38:39] offset:1024
	s_waitcnt lgkmcnt(1)
	global_store_dwordx4 v137, v[122:125], s[38:39] offset:2048
	s_waitcnt lgkmcnt(0)
	global_store_dwordx4 v137, v[126:129], s[38:39] offset:3072
	v_add_u32_e32 v137, 0x1000, v137
	ds_read_b32 v32, v136 offset:128
	s_waitcnt lgkmcnt(0)
	v_mul_f32_e32 v32, s42, v32
	s_waitcnt vmcnt(8)
	v_pk_mul_f32 v[66:67], v[66:67], v[32:33] op_sel_hi:[1,0]
	v_pk_mul_f32 v[68:69], v[68:69], v[32:33] op_sel_hi:[1,0]
	v_pk_mul_f32 v[82:83], v[82:83], v[32:33] op_sel_hi:[1,0]
	v_pk_mul_f32 v[84:85], v[84:85], v[32:33] op_sel_hi:[1,0]
	v_pk_mul_f32 v[130:131], v[66:67], v[102:103]
	v_pk_mul_f32 v[138:139], v[68:69], v[104:105]
	v_pk_mul_f32 v[102:103], v[82:83], v[102:103]
	v_pk_mul_f32 v[104:105], v[84:85], v[104:105]
	v_pk_fma_f32 v[66:67], v[66:67], v[98:99], v[102:103] neg_lo:[0,0,1] neg_hi:[0,0,1]
	v_pk_fma_f32 v[68:69], v[68:69], v[100:101], v[104:105] neg_lo:[0,0,1] neg_hi:[0,0,1]
	v_pk_fma_f32 v[82:83], v[82:83], v[98:99], v[130:131]
	v_pk_fma_f32 v[84:85], v[84:85], v[100:101], v[138:139]
	v_cvt_pk_bf16_f32 v130, v66, v67
	v_cvt_pk_bf16_f32 v131, v68, v69
	v_cvt_pk_bf16_f32 v138, v82, v83
	v_cvt_pk_bf16_f32 v139, v84, v85
	ds_write_b64 v134, v[130:131]
	ds_write_b64 v134, v[138:139] offset:64
	v_pk_mul_f32 v[70:71], v[70:71], v[32:33] op_sel_hi:[1,0]
	v_pk_mul_f32 v[72:73], v[72:73], v[32:33] op_sel_hi:[1,0]
	v_pk_mul_f32 v[86:87], v[86:87], v[32:33] op_sel_hi:[1,0]
	v_pk_mul_f32 v[88:89], v[88:89], v[32:33] op_sel_hi:[1,0]
	v_pk_mul_f32 v[130:131], v[70:71], v[118:119]
	v_pk_mul_f32 v[138:139], v[72:73], v[120:121]
	v_pk_mul_f32 v[118:119], v[86:87], v[118:119]
	v_pk_mul_f32 v[120:121], v[88:89], v[120:121]
	v_pk_fma_f32 v[70:71], v[70:71], v[114:115], v[118:119] neg_lo:[0,0,1] neg_hi:[0,0,1]
	v_pk_fma_f32 v[72:73], v[72:73], v[116:117], v[120:121] neg_lo:[0,0,1] neg_hi:[0,0,1]
	v_pk_fma_f32 v[86:87], v[86:87], v[114:115], v[130:131]
	v_pk_fma_f32 v[88:89], v[88:89], v[116:117], v[138:139]
	v_cvt_pk_bf16_f32 v130, v70, v71
	v_cvt_pk_bf16_f32 v131, v72, v73
	v_cvt_pk_bf16_f32 v138, v86, v87
	v_cvt_pk_bf16_f32 v139, v88, v89
	ds_write_b64 v134, v[130:131] offset:16
	ds_write_b64 v134, v[138:139] offset:80
	v_add_u32_e32 v132, 0x1000, v132
	global_load_dwordx4 v[106:109], v132, s[4:5]
	global_load_dwordx4 v[110:113], v132, s[6:7]
	global_load_dwordx4 v[122:125], v132, s[4:5] offset:32
	global_load_dwordx4 v[126:129], v132, s[6:7] offset:32
	s_waitcnt vmcnt(8)
; DI u32x2 pack4(float a, float b, float c, float d) { u32x2 w; w.x = pack2(a, b); w.y = pack2(c, d); return w; }
;   DI void rope(const f32x16 (&acc)[4][2], int row0, int r, int h, const float* sR, bf16_t* dst, int H, int hh, float scale, bf16_t* st) const {
;     ...
;     for (int mi = 0; mi < 4; ++mi) {
;       const int s = sb + mi * 32 + r;
;       const float rv = sR[mi * 32 + r] * scale;
; #pragma unroll
;       for (int g = 0; g < 4; ++g) {
;         const int d0 = 8 * g + 4 * h;
;         const f32x4 c = *(const f32x4*)(cosT + s * 32 + d0), sn = *(const f32x4*)(sinT + s * 32 + d0);
;         float o1[4], o2[4];
; #pragma unroll
;         for (int q = 0; q < 4; ++q) {
;           const float x1 = acc[mi][0][4 * g + q] * rv, x2 = acc[mi][1][4 * g + q] * rv;
;           o1[q] = x1 * c[q] - x2 * sn[q]; o2[q] = x1 * sn[q] + x2 * c[q];
;         }
;         *(u32x2*)(st + r * 72 + d0) = pack4(o1[0], o1[1], o1[2], o1[3]);
;         *(u32x2*)(st + r * 72 + 32 + d0) = pack4(o2[0], o2[1], o2[2], o2[3]);
;       }
;       flush_rows(st, dst + ((size_t)(b * H + hh) * S + sb + mi * 32) * 64, lane);
	v_pk_mul_f32 v[74:75], v[74:75], v[32:33] op_sel_hi:[1,0]
	v_pk_mul_f32 v[76:77], v[76:77], v[32:33] op_sel_hi:[1,0]
	v_pk_mul_f32 v[90:91], v[90:91], v[32:33] op_sel_hi:[1,0]
	v_pk_mul_f32 v[92:93], v[92:93], v[32:33] op_sel_hi:[1,0]
	v_pk_mul_f32 v[130:131], v[74:75], v[144:145]
	v_pk_mul_f32 v[138:139], v[76:77], v[146:147]
	v_pk_mul_f32 v[144:145], v[90:91], v[144:145]
	v_pk_mul_f32 v[146:147], v[92:93], v[146:147]
	v_pk_fma_f32 v[74:75], v[74:75], v[140:141], v[144:145] neg_lo:[0,0,1] neg_hi:[0,0,1]
	v_pk_fma_f32 v[76:77], v[76:77], v[142:143], v[146:147] neg_lo:[0,0,1] neg_hi:[0,0,1]
	v_pk_fma_f32 v[90:91], v[90:91], v[140:141], v[130:131]
	v_pk_fma_f32 v[92:93], v[92:93], v[142:143], v[138:139]
	v_cvt_pk_bf16_f32 v130, v74, v75
	v_cvt_pk_bf16_f32 v131, v76, v77
	v_cvt_pk_bf16_f32 v138, v90, v91
	v_cvt_pk_bf16_f32 v139, v92, v93
	ds_write_b64 v134, v[130:131] offset:32
	ds_write_b64 v134, v[138:139] offset:96
	v_pk_mul_f32 v[78:79], v[78:79], v[32:33] op_sel_hi:[1,0]
	v_pk_mul_f32 v[80:81], v[80:81], v[32:33] op_sel_hi:[1,0]
	v_pk_mul_f32 v[94:95], v[94:95], v[32:33] op_sel_hi:[1,0]
	v_pk_mul_f32 v[96:97], v[96:97], v[32:33] op_sel_hi:[1,0]
	v_pk_mul_f32 v[130:131], v[78:79], v[152:153]
	v_pk_mul_f32 v[138:139], v[80:81], v[154:155]
	v_pk_mul_f32 v[152:153], v[94:95], v[152:153]
	v_pk_mul_f32 v[154:155], v[96:97], v[154:155]
	v_pk_fma_f32 v[78:79], v[78:79], v[148:149], v[152:153] neg_lo:[0,0,1] neg_hi:[0,0,1]
	v_pk_fma_f32 v[80:81], v[80:81], v[150:151], v[154:155] neg_lo:[0,0,1] neg_hi:[0,0,1]
	v_pk_fma_f32 v[94:95], v[94:95], v[148:149], v[130:131]
	v_pk_fma_f32 v[96:97], v[96:97], v[150:151], v[138:139]
	v_cvt_pk_bf16_f32 v130, v78, v79
	v_cvt_pk_bf16_f32 v131, v80, v81
	v_cvt_pk_bf16_f32 v138, v94, v95
	v_cvt_pk_bf16_f32 v139, v96, v97
	ds_write_b64 v134, v[130:131] offset:48
	ds_write_b64 v134, v[138:139] offset:112
	global_load_dwordx4 v[98:101], v132, s[4:5] offset:64
	global_load_dwordx4 v[102:105], v132, s[6:7] offset:64
	global_load_dwordx4 v[114:117], v132, s[4:5] offset:96
	global_load_dwordx4 v[118:121], v132, s[6:7] offset:96
	ds_read_b128 v[66:69], v135
	ds_read_b128 v[70:73], v135 offset:1152
	ds_read_b128 v[82:85], v135 offset:2304
	ds_read_b128 v[86:89], v135 offset:3456
	s_waitcnt lgkmcnt(3)
	global_store_dwordx4 v137, v[66:69], s[38:39]
	s_waitcnt lgkmcnt(2)
	global_store_dwordx4 v137, v[70:73], s[38:39] offset:1024
	s_waitcnt lgkmcnt(1)
	global_store_dwordx4 v137, v[82:85], s[38:39] offset:2048
	s_waitcnt lgkmcnt(0)
	global_store_dwordx4 v137, v[86:89], s[38:39] offset:3072
	v_add_u32_e32 v137, 0x1000, v137
	ds_read_b32 v32, v136 offset:256
	s_waitcnt lgkmcnt(0)
	v_mul_f32_e32 v32, s42, v32
	s_waitcnt vmcnt(8)
	v_pk_mul_f32 v[34:35], v[34:35], v[32:33] op_sel_hi:[1,0]
	v_pk_mul_f32 v[36:37], v[36:37], v[32:33] op_sel_hi:[1,0]
	v_pk_mul_f32 v[50:51], v[50:51], v[32:33] op_sel_hi:[1,0]
	v_pk_mul_f32 v[52:53], v[52:53], v[32:33] op_sel_hi:[1,0]
	v_pk_mul_f32 v[130:131], v[34:35], v[110:111]
	v_pk_mul_f32 v[138:139], v[36:37], v[112:113]
	v_pk_mul_f32 v[110:111], v[50:51], v[110:111]
	v_pk_mul_f32 v[112:113], v[52:53], v[112:113]
	v_pk_fma_f32 v[34:35], v[34:35], v[106:107], v[110:111] neg_lo:[0,0,1] neg_hi:[0,0,1]
	v_pk_fma_f32 v[36:37], v[36:37], v[108:109], v[112:113] neg_lo:[0,0,1] neg_hi:[0,0,1]
	v_pk_fma_f32 v[50:51], v[50:51], v[106:107], v[130:131]
	v_pk_fma_f32 v[52:53], v[52:53], v[108:109], v[138:139]
	v_cvt_pk_bf16_f32 v130, v34, v35
	v_cvt_pk_bf16_f32 v131, v36, v37
	v_cvt_pk_bf16_f32 v138, v50, v51
	v_cvt_pk_bf16_f32 v139, v52, v53
	ds_write_b64 v134, v[130:131]
	ds_write_b64 v134, v[138:139] offset:64
	v_pk_mul_f32 v[38:39], v[38:39], v[32:33] op_sel_hi:[1,0]
	v_pk_mul_f32 v[40:41], v[40:41], v[32:33] op_sel_hi:[1,0]
	v_pk_mul_f32 v[54:55], v[54:55], v[32:33] op_sel_hi:[1,0]
	v_pk_mul_f32 v[56:57], v[56:57], v[32:33] op_sel_hi:[1,0]
	v_pk_mul_f32 v[130:131], v[38:39], v[126:127]
	v_pk_mul_f32 v[138:139], v[40:41], v[128:129]
	v_pk_mul_f32 v[126:127], v[54:55], v[126:127]
	v_pk_mul_f32 v[128:129], v[56:57], v[128:129]
	v_pk_fma_f32 v[38:39], v[38:39], v[122:123], v[126:127] neg_lo:[0,0,1] neg_hi:[0,0,1]
	v_pk_fma_f32 v[40:41], v[40:41], v[124:125], v[128:129] neg_lo:[0,0,1] neg_hi:[0,0,1]
	v_pk_fma_f32 v[54:55], v[54:55], v[122:123], v[130:131]
	v_pk_fma_f32 v[56:57], v[56:57], v[124:125], v[138:139]
	v_cvt_pk_bf16_f32 v130, v38, v39
	v_cvt_pk_bf16_f32 v131, v40, v41
	v_cvt_pk_bf16_f32 v138, v54, v55
	v_cvt_pk_bf16_f32 v139, v56, v57
	ds_write_b64 v134, v[130:131] offset:16
	ds_write_b64 v134, v[138:139] offset:80
	v_add_u32_e32 v132, 0x1000, v132
	global_load_dwordx4 v[140:143], v132, s[4:5]
	global_load_dwordx4 v[144:147], v132, s[6:7]
	global_load_dwordx4 v[148:151], v132, s[4:5] offset:32
	global_load_dwordx4 v[152:155], v132, s[6:7] offset:32
	s_waitcnt vmcnt(8)
; DI u32x2 pack4(float a, float b, float c, float d) { u32x2 w; w.x = pack2(a, b); w.y = pack2(c, d); return w; }
;   DI void rope(const f32x16 (&acc)[4][2], int row0, int r, int h, const float* sR, bf16_t* dst, int H, int hh, float scale, bf16_t* st) const {
;     ...
;     for (int mi = 0; mi < 4; ++mi) {
;       const int s = sb + mi * 32 + r;
;       const float rv = sR[mi * 32 + r] * scale;
; #pragma unroll
;       for (int g = 0; g < 4; ++g) {
;         const int d0 = 8 * g + 4 * h;
;         const f32x4 c = *(const f32x4*)(cosT + s * 32 + d0), sn = *(const f32x4*)(sinT + s * 32 + d0);
;         float o1[4], o2[4];
; #pragma unroll
;         for (int q = 0; q < 4; ++q) {
;           const float x1 = acc[mi][0][4 * g + q] * rv, x2 = acc[mi][1][4 * g + q] * rv;
;           o1[q] = x1 * c[q] - x2 * sn[q]; o2[q] = x1 * sn[q] + x2 * c[q];
;         }
;         *(u32x2*)(st + r * 72 + d0) = pack4(o1[0], o1[1], o1[2], o1[3]);
;         *(u32x2*)(st + r * 72 + 32 + d0) = pack4(o2[0], o2[1], o2[2], o2[3]);
;       }
;       flush_rows(st, dst + ((size_t)(b * H + hh) * S + sb + mi * 32) * 64, lane);
;     }
;   }
	v_pk_mul_f32 v[42:43], v[42:43], v[32:33] op_sel_hi:[1,0]
	v_pk_mul_f32 v[44:45], v[44:45], v[32:33] op_sel_hi:[1,0]
	v_pk_mul_f32 v[58:59], v[58:59], v[32:33] op_sel_hi:[1,0]
	v_pk_mul_f32 v[60:61], v[60:61], v[32:33] op_sel_hi:[1,0]
	v_pk_mul_f32 v[130:131], v[42:43], v[102:103]
	v_pk_mul_f32 v[138:139], v[44:45], v[104:105]
	v_pk_mul_f32 v[102:103], v[58:59], v[102:103]
	v_pk_mul_f32 v[104:105], v[60:61], v[104:105]
	v_pk_fma_f32 v[42:43], v[42:43], v[98:99], v[102:103] neg_lo:[0,0,1] neg_hi:[0,0,1]
	v_pk_fma_f32 v[44:45], v[44:45], v[100:101], v[104:105] neg_lo:[0,0,1] neg_hi:[0,0,1]
	v_pk_fma_f32 v[58:59], v[58:59], v[98:99], v[130:131]
	v_pk_fma_f32 v[60:61], v[60:61], v[100:101], v[138:139]
	v_cvt_pk_bf16_f32 v130, v42, v43
	v_cvt_pk_bf16_f32 v131, v44, v45
	v_cvt_pk_bf16_f32 v138, v58, v59
	v_cvt_pk_bf16_f32 v139, v60, v61
	ds_write_b64 v134, v[130:131] offset:32
	ds_write_b64 v134, v[138:139] offset:96
	v_pk_mul_f32 v[46:47], v[46:47], v[32:33] op_sel_hi:[1,0]
	v_pk_mul_f32 v[48:49], v[48:49], v[32:33] op_sel_hi:[1,0]
	v_pk_mul_f32 v[62:63], v[62:63], v[32:33] op_sel_hi:[1,0]
	v_pk_mul_f32 v[64:65], v[64:65], v[32:33] op_sel_hi:[1,0]
	v_pk_mul_f32 v[130:131], v[46:47], v[118:119]
	v_pk_mul_f32 v[138:139], v[48:49], v[120:121]
	v_pk_mul_f32 v[118:119], v[62:63], v[118:119]
	v_pk_mul_f32 v[120:121], v[64:65], v[120:121]
	v_pk_fma_f32 v[46:47], v[46:47], v[114:115], v[118:119] neg_lo:[0,0,1] neg_hi:[0,0,1]
	v_pk_fma_f32 v[48:49], v[48:49], v[116:117], v[120:121] neg_lo:[0,0,1] neg_hi:[0,0,1]
	v_pk_fma_f32 v[62:63], v[62:63], v[114:115], v[130:131]
	v_pk_fma_f32 v[64:65], v[64:65], v[116:117], v[138:139]
	v_cvt_pk_bf16_f32 v130, v46, v47
	v_cvt_pk_bf16_f32 v131, v48, v49
	v_cvt_pk_bf16_f32 v138, v62, v63
	v_cvt_pk_bf16_f32 v139, v64, v65
	ds_write_b64 v134, v[130:131] offset:48
	ds_write_b64 v134, v[138:139] offset:112
	global_load_dwordx4 v[74:77], v132, s[4:5] offset:64
	global_load_dwordx4 v[78:81], v132, s[6:7] offset:64
	global_load_dwordx4 v[90:93], v132, s[4:5] offset:96
	global_load_dwordx4 v[94:97], v132, s[6:7] offset:96
	ds_read_b128 v[66:69], v135
	ds_read_b128 v[70:73], v135 offset:1152
	ds_read_b128 v[82:85], v135 offset:2304
	ds_read_b128 v[86:89], v135 offset:3456
	s_waitcnt lgkmcnt(3)
	global_store_dwordx4 v137, v[66:69], s[38:39]
	s_waitcnt lgkmcnt(2)
	global_store_dwordx4 v137, v[70:73], s[38:39] offset:1024
	s_waitcnt lgkmcnt(1)
	global_store_dwordx4 v137, v[82:85], s[38:39] offset:2048
	s_waitcnt lgkmcnt(0)
	global_store_dwordx4 v137, v[86:89], s[38:39] offset:3072
	v_add_u32_e32 v137, 0x1000, v137
	ds_read_b32 v32, v136 offset:384
	s_waitcnt lgkmcnt(0)
	v_mul_f32_e32 v32, s42, v32
	s_waitcnt vmcnt(8)
	v_pk_mul_f32 v[0:1], v[0:1], v[32:33] op_sel_hi:[1,0]
	v_pk_mul_f32 v[2:3], v[2:3], v[32:33] op_sel_hi:[1,0]
	v_pk_mul_f32 v[16:17], v[16:17], v[32:33] op_sel_hi:[1,0]
	v_pk_mul_f32 v[18:19], v[18:19], v[32:33] op_sel_hi:[1,0]
	v_pk_mul_f32 v[130:131], v[0:1], v[144:145]
	v_pk_mul_f32 v[138:139], v[2:3], v[146:147]
	v_pk_mul_f32 v[144:145], v[16:17], v[144:145]
	v_pk_mul_f32 v[146:147], v[18:19], v[146:147]
	v_pk_fma_f32 v[0:1], v[0:1], v[140:141], v[144:145] neg_lo:[0,0,1] neg_hi:[0,0,1]
	v_pk_fma_f32 v[2:3], v[2:3], v[142:143], v[146:147] neg_lo:[0,0,1] neg_hi:[0,0,1]
	v_pk_fma_f32 v[16:17], v[16:17], v[140:141], v[130:131]
	v_pk_fma_f32 v[18:19], v[18:19], v[142:143], v[138:139]
	v_cvt_pk_bf16_f32 v130, v0, v1
	v_cvt_pk_bf16_f32 v131, v2, v3
	v_cvt_pk_bf16_f32 v138, v16, v17
	v_cvt_pk_bf16_f32 v139, v18, v19
	ds_write_b64 v134, v[130:131]
	ds_write_b64 v134, v[138:139] offset:64
	v_pk_mul_f32 v[4:5], v[4:5], v[32:33] op_sel_hi:[1,0]
	v_pk_mul_f32 v[6:7], v[6:7], v[32:33] op_sel_hi:[1,0]
	v_pk_mul_f32 v[20:21], v[20:21], v[32:33] op_sel_hi:[1,0]
	v_pk_mul_f32 v[22:23], v[22:23], v[32:33] op_sel_hi:[1,0]
	v_pk_mul_f32 v[130:131], v[4:5], v[152:153]
	v_pk_mul_f32 v[138:139], v[6:7], v[154:155]
	v_pk_mul_f32 v[152:153], v[20:21], v[152:153]
	v_pk_mul_f32 v[154:155], v[22:23], v[154:155]
	v_pk_fma_f32 v[4:5], v[4:5], v[148:149], v[152:153] neg_lo:[0,0,1] neg_hi:[0,0,1]
	v_pk_fma_f32 v[6:7], v[6:7], v[150:151], v[154:155] neg_lo:[0,0,1] neg_hi:[0,0,1]
	v_pk_fma_f32 v[20:21], v[20:21], v[148:149], v[130:131]
	v_pk_fma_f32 v[22:23], v[22:23], v[150:151], v[138:139]
	v_cvt_pk_bf16_f32 v130, v4, v5
	v_cvt_pk_bf16_f32 v131, v6, v7
	v_cvt_pk_bf16_f32 v138, v20, v21
	v_cvt_pk_bf16_f32 v139, v22, v23
	ds_write_b64 v134, v[130:131] offset:16
	ds_write_b64 v134, v[138:139] offset:80
	s_waitcnt vmcnt(4)
	v_pk_mul_f32 v[8:9], v[8:9], v[32:33] op_sel_hi:[1,0]
	v_pk_mul_f32 v[10:11], v[10:11], v[32:33] op_sel_hi:[1,0]
	v_pk_mul_f32 v[24:25], v[24:25], v[32:33] op_sel_hi:[1,0]
	v_pk_mul_f32 v[26:27], v[26:27], v[32:33] op_sel_hi:[1,0]
	v_pk_mul_f32 v[130:131], v[8:9], v[78:79]
	v_pk_mul_f32 v[138:139], v[10:11], v[80:81]
	v_pk_mul_f32 v[78:79], v[24:25], v[78:79]
	v_pk_mul_f32 v[80:81], v[26:27], v[80:81]
	v_pk_fma_f32 v[8:9], v[8:9], v[74:75], v[78:79] neg_lo:[0,0,1] neg_hi:[0,0,1]
	v_pk_fma_f32 v[10:11], v[10:11], v[76:77], v[80:81] neg_lo:[0,0,1] neg_hi:[0,0,1]
	v_pk_fma_f32 v[24:25], v[24:25], v[74:75], v[130:131]
	v_pk_fma_f32 v[26:27], v[26:27], v[76:77], v[138:139]
	v_cvt_pk_bf16_f32 v130, v8, v9
	v_cvt_pk_bf16_f32 v131, v10, v11
	v_cvt_pk_bf16_f32 v138, v24, v25
	v_cvt_pk_bf16_f32 v139, v26, v27
	ds_write_b64 v134, v[130:131] offset:32
	ds_write_b64 v134, v[138:139] offset:96
	v_pk_mul_f32 v[12:13], v[12:13], v[32:33] op_sel_hi:[1,0]
	v_pk_mul_f32 v[14:15], v[14:15], v[32:33] op_sel_hi:[1,0]
	v_pk_mul_f32 v[28:29], v[28:29], v[32:33] op_sel_hi:[1,0]
	v_pk_mul_f32 v[30:31], v[30:31], v[32:33] op_sel_hi:[1,0]
	v_pk_mul_f32 v[130:131], v[12:13], v[94:95]
	v_pk_mul_f32 v[138:139], v[14:15], v[96:97]
	v_pk_mul_f32 v[94:95], v[28:29], v[94:95]
	v_pk_mul_f32 v[96:97], v[30:31], v[96:97]
	v_pk_fma_f32 v[12:13], v[12:13], v[90:91], v[94:95] neg_lo:[0,0,1] neg_hi:[0,0,1]
	v_pk_fma_f32 v[14:15], v[14:15], v[92:93], v[96:97] neg_lo:[0,0,1] neg_hi:[0,0,1]
	v_pk_fma_f32 v[28:29], v[28:29], v[90:91], v[130:131]
	v_pk_fma_f32 v[30:31], v[30:31], v[92:93], v[138:139]
	v_cvt_pk_bf16_f32 v130, v12, v13
	v_cvt_pk_bf16_f32 v131, v14, v15
	v_cvt_pk_bf16_f32 v138, v28, v29
	v_cvt_pk_bf16_f32 v139, v30, v31
	ds_write_b64 v134, v[130:131] offset:48
	ds_write_b64 v134, v[138:139] offset:112
	ds_read_b128 v[106:109], v135
	ds_read_b128 v[110:113], v135 offset:1152
	ds_read_b128 v[122:125], v135 offset:2304
	ds_read_b128 v[126:129], v135 offset:3456
	s_waitcnt lgkmcnt(3)
	global_store_dwordx4 v137, v[106:109], s[38:39]
	s_waitcnt lgkmcnt(2)
	global_store_dwordx4 v137, v[110:113], s[38:39] offset:1024
	s_waitcnt lgkmcnt(1)
	global_store_dwordx4 v137, v[122:125], s[38:39] offset:2048
	s_waitcnt lgkmcnt(0)
	global_store_dwordx4 v137, v[126:129], s[38:39] offset:3072
	s_mov_b32 s50, 0x80000
	s_mov_b32 s51, 0x100000
	s_mov_b32 s52, 0x40000
	s_mov_b32 s55, 0x20000
	s_mov_b32 s56, 0x200000
	s_mov_b32 s57, 0x400000
	s_mov_b64 s[36:37], exec
	s_branch .LBB0_627
;   DI void operator()(const f32x16 (&acc)[4][2], bool vt, int row0, int col0, int r, int h, const float* sR, float* stage) const {
;     const int seg = col0 >> 6;
;     bf16_t* st = (bf16_t*)stage;
;     if (seg < 8) rope(acc, row0, r, h, sR, eb.QN, 8, seg, 0.125f, st);
;     else if (seg < 10) rope(acc, row0, r, h, sR, eb.KC, 2, seg - 8, 1.f, st);
;     else if (seg < 12) rowmajor(acc, row0, r, h, sR, eb.VC, 2, seg - 10, 1.f, st);
;     else if (seg < 14) rope(acc, row0, r, h, sR, eb.KS, 2, seg - 12, 1.f, st);
;     else if (seg < 16) transposed(acc, row0, r, h, sR, eb.VST, 2, seg - 14, st);
;     else if (seg < 18) rope(acc, row0, r, h, sR, eb.KW, 2, seg - 16, 1.f, st);
;     else if (seg < 20) transposed(acc, row0, r, h, sR, eb.VWT, 2, seg - 18, st);
;     else if (seg < 28) rope(acc, row0, r, h, sR, eb.DQ, 8, seg - 20, 0.125f, st);
;     else if (seg < 36) rope(acc, row0, r, h, sR, eb.DK, 8, seg - 28, 1.f, st);
;     else if (seg < 44) transposed(acc, row0, r, h, sR, eb.DVT, 8, seg - 36, st);
;     else if (seg == 44) {
; #pragma unroll
;       for (int mi = 0; mi < 4; ++mi) {
;         const int row = row0 + mi * 32 + r;
;         const float rv = sR[mi * 32 + r];
; #pragma unroll
;         for (int g = 0; g < 3; ++g) {
;           f32x4 o;
; #pragma unroll
;           for (int q = 0; q < 4; ++q) o[q] = 1.f / (1.f + __expf(-acc[mi][0][4 * g + q] * rv));
;           *(f32x4*)(eb.gate + (size_t)row * 24 + 8 * g + 4 * h) = o;
.Lrope_skip:
	s_and_saveexec_b64 s[36:37], vcc
	s_xor_b64 s[36:37], exec, s[36:37]
	s_mov_b32 s55, 0x20000
	s_mov_b32 s52, 0x40000
	s_mov_b32 s50, 0x80000
	s_mov_b32 s51, 0x100000
	s_cbranch_execz .LBB0_699
	v_cmp_lt_u32_e32 vcc, 9, v132
	s_and_saveexec_b64 s[38:39], vcc
	s_xor_b64 s[38:39], exec, s[38:39]
	s_cbranch_execz .LBB0_696
	v_cmp_lt_u32_e32 vcc, 11, v132
	s_and_saveexec_b64 s[40:41], vcc
	s_xor_b64 s[40:41], exec, s[40:41]
	s_cbranch_execz .LBB0_693
	v_cmp_lt_u32_e32 vcc, 13, v132
	s_and_saveexec_b64 s[42:43], vcc
	s_xor_b64 s[42:43], exec, s[42:43]
	s_cbranch_execz .LBB0_690
	v_cmp_lt_u32_e32 vcc, 15, v132
	s_and_saveexec_b64 s[44:45], vcc
	s_xor_b64 s[44:45], exec, s[44:45]
	s_cbranch_execz .LBB0_687
	v_cmp_lt_u32_e32 vcc, 17, v132
	s_and_saveexec_b64 s[46:47], vcc
	s_xor_b64 s[46:47], exec, s[46:47]
	s_cbranch_execz .LBB0_684
	v_cmp_lt_u32_e32 vcc, 19, v132
	s_and_saveexec_b64 s[48:49], vcc
	s_xor_b64 s[48:49], exec, s[48:49]
	s_cbranch_execz .LBB0_681
	v_cmp_lt_u32_e32 vcc, 27, v132
	s_and_saveexec_b64 s[50:51], vcc
	s_xor_b64 s[50:51], exec, s[50:51]
	s_cbranch_execz .LBB0_678
	v_cmp_lt_u32_e32 vcc, 35, v132
	s_and_saveexec_b64 s[52:53], vcc
	s_xor_b64 s[52:53], exec, s[52:53]
	s_cbranch_execz .LBB0_675
	v_cmp_lt_u32_e32 vcc, 43, v132
	s_and_saveexec_b64 s[54:55], vcc
	s_xor_b64 s[54:55], exec, s[54:55]
	s_cbranch_execz .LBB0_672
	s_movk_i32 s33, 0xb00
	v_cmp_eq_u32_e32 vcc, s33, v32
	s_and_saveexec_b64 s[56:57], vcc
	s_cbranch_execz .LBB0_671
	v_lshl_add_u32 v17, v153, 2, v136
	ds_read_b32 v22, v17
	v_or_b32_e32 v16, v133, v153
	s_movk_i32 s33, 0x60
	v_lshlrev_b32_e32 v32, 4, v152
	s_waitcnt lgkmcnt(0)
	v_mul_f32_e64 v14, v22, -v100
	v_mul_f32_e64 v15, v22, -v101
	v_mul_f32_e32 v14, 0x3fb8aa3b, v14
	v_mul_f32_e32 v15, 0x3fb8aa3b, v15
	v_exp_f32_e32 v14, v14
	v_exp_f32_e32 v15, v15
	v_mul_f32_e64 v12, v22, -v98
	v_mul_f32_e64 v13, v22, -v99
	v_mul_f32_e32 v12, 0x3fb8aa3b, v12
	v_pk_add_f32 v[14:15], v[14:15], 1.0 op_sel_hi:[1,0]
	v_mul_f32_e32 v13, 0x3fb8aa3b, v13
	v_div_scale_f32 v18, s[68:69], v15, v15, 1.0
	v_rcp_f32_e32 v19, v18
	v_exp_f32_e32 v12, v12
	v_exp_f32_e32 v13, v13
	v_fma_f32 v20, -v18, v19, 1.0
	v_fmac_f32_e32 v19, v20, v19
	v_div_scale_f32 v20, vcc, 1.0, v15, 1.0
	v_mul_f32_e32 v21, v20, v19
	v_fma_f32 v23, -v18, v21, v20
	v_fmac_f32_e32 v21, v23, v19
	v_fma_f32 v18, -v18, v21, v20
	v_div_fmas_f32 v18, v18, v19, v21
	v_div_fixup_f32 v21, v18, v15, 1.0
	v_div_scale_f32 v15, s[68:69], v14, v14, 1.0
	v_rcp_f32_e32 v18, v15
	v_pk_add_f32 v[12:13], v[12:13], 1.0 op_sel_hi:[1,0]
	v_fma_f32 v19, -v15, v18, 1.0
	v_fmac_f32_e32 v18, v19, v18
	v_div_scale_f32 v19, vcc, 1.0, v14, 1.0
	v_mul_f32_e32 v20, v19, v18
	v_fma_f32 v23, -v15, v20, v19
	v_fmac_f32_e32 v20, v23, v18
	v_fma_f32 v15, -v15, v20, v19
	v_div_fmas_f32 v15, v15, v18, v20
	v_div_fixup_f32 v20, v15, v14, 1.0
	v_div_scale_f32 v14, s[68:69], v13, v13, 1.0
	v_rcp_f32_e32 v15, v14
	s_nop 0
	v_fma_f32 v18, -v14, v15, 1.0
	v_fmac_f32_e32 v15, v18, v15
	v_div_scale_f32 v18, vcc, 1.0, v13, 1.0
	v_mul_f32_e32 v19, v18, v15
	v_fma_f32 v23, -v14, v19, v18
	v_fmac_f32_e32 v19, v23, v15
	v_fma_f32 v14, -v14, v19, v18
	v_div_fmas_f32 v14, v14, v15, v19
	v_div_fixup_f32 v19, v14, v13, 1.0
	v_div_scale_f32 v13, s[68:69], v12, v12, 1.0
	v_rcp_f32_e32 v14, v13
	s_nop 0
	v_fma_f32 v15, -v13, v14, 1.0
	v_fmac_f32_e32 v14, v15, v14
	v_div_scale_f32 v15, vcc, 1.0, v12, 1.0
	v_mul_f32_e32 v18, v15, v14
	v_fma_f32 v23, -v13, v18, v15
	v_fmac_f32_e32 v18, v23, v14
	v_fma_f32 v13, -v13, v18, v15
	v_div_fmas_f32 v13, v13, v14, v18
	v_div_fixup_f32 v18, v13, v12, 1.0
	v_mov_b64_e32 v[12:13], s[26:27]
	v_mad_i64_i32 v[14:15], s[68:69], v16, s33, v[12:13]
	v_lshl_add_u64 v[14:15], v[14:15], 0, v[32:33]
	flat_store_dwordx4 v[14:15], v[18:21]
	s_nop 1
	v_mul_f32_e64 v20, v22, -v104
	v_mul_f32_e64 v21, v22, -v105
	v_mul_f32_e32 v20, 0x3fb8aa3b, v20
	v_mul_f32_e32 v21, 0x3fb8aa3b, v21
	v_exp_f32_e32 v20, v20
	v_exp_f32_e32 v21, v21
	v_mul_f32_e64 v18, v22, -v102
	v_mul_f32_e64 v19, v22, -v103
	v_mul_f32_e32 v18, 0x3fb8aa3b, v18
	v_pk_add_f32 v[20:21], v[20:21], 1.0 op_sel_hi:[1,0]
	v_mul_f32_e32 v19, 0x3fb8aa3b, v19
	v_div_scale_f32 v23, s[68:69], v21, v21, 1.0
	v_rcp_f32_e32 v24, v23
	v_exp_f32_e32 v18, v18
	v_exp_f32_e32 v19, v19
	v_fma_f32 v25, -v23, v24, 1.0
	v_fmac_f32_e32 v24, v25, v24
	v_div_scale_f32 v25, vcc, 1.0, v21, 1.0
	v_mul_f32_e32 v26, v25, v24
	v_fma_f32 v27, -v23, v26, v25
	v_fmac_f32_e32 v26, v27, v24
	v_fma_f32 v23, -v23, v26, v25
	v_div_fmas_f32 v23, v23, v24, v26
	v_div_fixup_f32 v21, v23, v21, 1.0
	v_div_scale_f32 v23, s[68:69], v20, v20, 1.0
	v_rcp_f32_e32 v24, v23
	v_pk_add_f32 v[18:19], v[18:19], 1.0 op_sel_hi:[1,0]
	v_fma_f32 v25, -v23, v24, 1.0
	v_fmac_f32_e32 v24, v25, v24
	v_div_scale_f32 v25, vcc, 1.0, v20, 1.0
	v_mul_f32_e32 v26, v25, v24
	v_fma_f32 v27, -v23, v26, v25
	v_fmac_f32_e32 v26, v27, v24
	v_fma_f32 v23, -v23, v26, v25
	v_div_fmas_f32 v23, v23, v24, v26
	v_div_fixup_f32 v20, v23, v20, 1.0
	v_div_scale_f32 v23, s[68:69], v19, v19, 1.0
	v_rcp_f32_e32 v24, v23
	s_nop 0
	v_fma_f32 v25, -v23, v24, 1.0
	v_fmac_f32_e32 v24, v25, v24
	v_div_scale_f32 v25, vcc, 1.0, v19, 1.0
	v_mul_f32_e32 v26, v25, v24
	v_fma_f32 v27, -v23, v26, v25
	v_fmac_f32_e32 v26, v27, v24
	v_fma_f32 v23, -v23, v26, v25
	v_div_fmas_f32 v23, v23, v24, v26
	v_div_fixup_f32 v19, v23, v19, 1.0
	v_div_scale_f32 v23, s[68:69], v18, v18, 1.0
	v_rcp_f32_e32 v24, v23
	s_nop 0
	v_fma_f32 v25, -v23, v24, 1.0
	v_fmac_f32_e32 v24, v25, v24
	v_div_scale_f32 v25, vcc, 1.0, v18, 1.0
	v_mul_f32_e32 v26, v25, v24
	v_fma_f32 v27, -v23, v26, v25
	v_fmac_f32_e32 v26, v27, v24
	v_fma_f32 v23, -v23, v26, v25
;   DI void operator()(const f32x16 (&acc)[4][2], bool vt, int row0, int col0, int r, int h, const float* sR, float* stage) const {
;     ...
;     else if (seg == 44) {
; #pragma unroll
;       for (int mi = 0; mi < 4; ++mi) {
;         const int row = row0 + mi * 32 + r;
;         const float rv = sR[mi * 32 + r];
; #pragma unroll
;         for (int g = 0; g < 3; ++g) {
;           f32x4 o;
; #pragma unroll
;           for (int q = 0; q < 4; ++q) o[q] = 1.f / (1.f + __expf(-acc[mi][0][4 * g + q] * rv));
;           *(f32x4*)(eb.gate + (size_t)row * 24 + 8 * g + 4 * h) = o;
;         }
;       }
	v_div_fmas_f32 v23, v23, v24, v26
	v_div_fixup_f32 v18, v23, v18, 1.0
	flat_store_dwordx4 v[14:15], v[18:21] offset:32
	s_nop 1
	v_mul_f32_e64 v20, v22, -v108
	v_mul_f32_e64 v21, v22, -v109
	v_mul_f32_e32 v20, 0x3fb8aa3b, v20
	v_mul_f32_e32 v21, 0x3fb8aa3b, v21
	v_exp_f32_e32 v20, v20
	v_exp_f32_e32 v21, v21
	v_mul_f32_e64 v18, v22, -v106
	v_mul_f32_e64 v19, v22, -v107
	v_mul_f32_e32 v18, 0x3fb8aa3b, v18
	v_pk_add_f32 v[20:21], v[20:21], 1.0 op_sel_hi:[1,0]
	v_mul_f32_e32 v19, 0x3fb8aa3b, v19
	v_div_scale_f32 v22, s[68:69], v21, v21, 1.0
	v_rcp_f32_e32 v23, v22
	v_exp_f32_e32 v18, v18
	v_exp_f32_e32 v19, v19
	v_fma_f32 v24, -v22, v23, 1.0
	v_fmac_f32_e32 v23, v24, v23
	v_div_scale_f32 v24, vcc, 1.0, v21, 1.0
	v_mul_f32_e32 v25, v24, v23
	v_fma_f32 v26, -v22, v25, v24
	v_fmac_f32_e32 v25, v26, v23
	v_fma_f32 v22, -v22, v25, v24
	v_div_fmas_f32 v22, v22, v23, v25
	v_div_fixup_f32 v21, v22, v21, 1.0
	v_div_scale_f32 v22, s[68:69], v20, v20, 1.0
	v_rcp_f32_e32 v23, v22
	v_pk_add_f32 v[18:19], v[18:19], 1.0 op_sel_hi:[1,0]
	v_fma_f32 v24, -v22, v23, 1.0
	v_fmac_f32_e32 v23, v24, v23
	v_div_scale_f32 v24, vcc, 1.0, v20, 1.0
	v_mul_f32_e32 v25, v24, v23
	v_fma_f32 v26, -v22, v25, v24
	v_fmac_f32_e32 v25, v26, v23
	v_fma_f32 v22, -v22, v25, v24
	v_div_fmas_f32 v22, v22, v23, v25
	v_div_fixup_f32 v20, v22, v20, 1.0
	v_div_scale_f32 v22, s[68:69], v19, v19, 1.0
	v_rcp_f32_e32 v23, v22
	s_nop 0
	v_fma_f32 v24, -v22, v23, 1.0
	v_fmac_f32_e32 v23, v24, v23
	v_div_scale_f32 v24, vcc, 1.0, v19, 1.0
	v_mul_f32_e32 v25, v24, v23
	v_fma_f32 v26, -v22, v25, v24
	v_fmac_f32_e32 v25, v26, v23
	v_fma_f32 v22, -v22, v25, v24
	v_div_fmas_f32 v22, v22, v23, v25
	v_div_fixup_f32 v19, v22, v19, 1.0
	v_div_scale_f32 v22, s[68:69], v18, v18, 1.0
	v_rcp_f32_e32 v23, v22
	s_nop 0
	v_fma_f32 v24, -v22, v23, 1.0
	v_fmac_f32_e32 v23, v24, v23
	v_div_scale_f32 v24, vcc, 1.0, v18, 1.0
	v_mul_f32_e32 v25, v24, v23
	v_fma_f32 v26, -v22, v25, v24
	v_fmac_f32_e32 v25, v26, v23
	v_fma_f32 v22, -v22, v25, v24
	v_div_fmas_f32 v22, v22, v23, v25
	v_div_fixup_f32 v18, v22, v18, 1.0
	flat_store_dwordx4 v[14:15], v[18:21] offset:64
	ds_read_b32 v23, v17 offset:128
	v_or_b32_e32 v22, 32, v16
	s_waitcnt lgkmcnt(0)
	v_mul_f32_e64 v18, v23, -v68
	v_mul_f32_e64 v19, v23, -v69
	v_mul_f32_e32 v18, 0x3fb8aa3b, v18
	v_mul_f32_e32 v19, 0x3fb8aa3b, v19
	v_exp_f32_e32 v18, v18
	v_exp_f32_e32 v19, v19
	v_mul_f32_e64 v14, v23, -v66
	v_mul_f32_e64 v15, v23, -v67
	v_mul_f32_e32 v14, 0x3fb8aa3b, v14
	v_pk_add_f32 v[18:19], v[18:19], 1.0 op_sel_hi:[1,0]
	v_mul_f32_e32 v15, 0x3fb8aa3b, v15
	v_div_scale_f32 v20, s[68:69], v19, v19, 1.0
	v_rcp_f32_e32 v21, v20
	v_exp_f32_e32 v14, v14
	v_exp_f32_e32 v15, v15
	v_fma_f32 v24, -v20, v21, 1.0
	v_fmac_f32_e32 v21, v24, v21
	v_div_scale_f32 v24, vcc, 1.0, v19, 1.0
	v_mul_f32_e32 v25, v24, v21
	v_fma_f32 v26, -v20, v25, v24
	v_fmac_f32_e32 v25, v26, v21
	v_fma_f32 v20, -v20, v25, v24
	v_div_fmas_f32 v20, v20, v21, v25
	v_div_fixup_f32 v21, v20, v19, 1.0
	v_div_scale_f32 v19, s[68:69], v18, v18, 1.0
	v_rcp_f32_e32 v20, v19
	v_pk_add_f32 v[14:15], v[14:15], 1.0 op_sel_hi:[1,0]
	v_fma_f32 v24, -v19, v20, 1.0
	v_fmac_f32_e32 v20, v24, v20
	v_div_scale_f32 v24, vcc, 1.0, v18, 1.0
	v_mul_f32_e32 v25, v24, v20
	v_fma_f32 v26, -v19, v25, v24
	v_fmac_f32_e32 v25, v26, v20
	v_fma_f32 v19, -v19, v25, v24
	v_div_fmas_f32 v19, v19, v20, v25
	v_div_fixup_f32 v20, v19, v18, 1.0
	v_div_scale_f32 v18, s[68:69], v15, v15, 1.0
	v_rcp_f32_e32 v19, v18
	s_nop 0
	v_fma_f32 v24, -v18, v19, 1.0
	v_fmac_f32_e32 v19, v24, v19
	v_div_scale_f32 v24, vcc, 1.0, v15, 1.0
	v_mul_f32_e32 v25, v24, v19
	v_fma_f32 v26, -v18, v25, v24
	v_fmac_f32_e32 v25, v26, v19
	v_fma_f32 v18, -v18, v25, v24
	v_div_fmas_f32 v18, v18, v19, v25
	v_div_fixup_f32 v19, v18, v15, 1.0
	v_div_scale_f32 v15, s[68:69], v14, v14, 1.0
	v_rcp_f32_e32 v18, v15
	s_nop 0
	v_fma_f32 v24, -v15, v18, 1.0
	v_fmac_f32_e32 v18, v24, v18
	v_div_scale_f32 v24, vcc, 1.0, v14, 1.0
	v_mul_f32_e32 v25, v24, v18
	v_fma_f32 v26, -v15, v25, v24
	v_fmac_f32_e32 v25, v26, v18
	v_fma_f32 v15, -v15, v25, v24
	v_div_fmas_f32 v15, v15, v18, v25
	v_div_fixup_f32 v18, v15, v14, 1.0
	v_mad_i64_i32 v[14:15], s[68:69], v22, s33, v[12:13]
	v_lshl_add_u64 v[14:15], v[14:15], 0, v[32:33]
	flat_store_dwordx4 v[14:15], v[18:21]
	s_nop 1
	v_mul_f32_e64 v20, v23, -v72
	v_mul_f32_e64 v21, v23, -v73
	v_mul_f32_e32 v20, 0x3fb8aa3b, v20
	v_mul_f32_e32 v21, 0x3fb8aa3b, v21
	v_exp_f32_e32 v20, v20
	v_exp_f32_e32 v21, v21
	v_mul_f32_e64 v18, v23, -v70
	v_mul_f32_e64 v19, v23, -v71
	v_mul_f32_e32 v18, 0x3fb8aa3b, v18
	v_pk_add_f32 v[20:21], v[20:21], 1.0 op_sel_hi:[1,0]
	v_mul_f32_e32 v19, 0x3fb8aa3b, v19
	v_div_scale_f32 v22, s[68:69], v21, v21, 1.0
	v_rcp_f32_e32 v24, v22
	v_exp_f32_e32 v18, v18
	v_exp_f32_e32 v19, v19
	v_fma_f32 v25, -v22, v24, 1.0
	v_fmac_f32_e32 v24, v25, v24
	v_div_scale_f32 v25, vcc, 1.0, v21, 1.0
	v_mul_f32_e32 v26, v25, v24
	v_fma_f32 v27, -v22, v26, v25
	v_fmac_f32_e32 v26, v27, v24
	v_fma_f32 v22, -v22, v26, v25
	v_div_fmas_f32 v22, v22, v24, v26
	v_div_fixup_f32 v21, v22, v21, 1.0
	v_div_scale_f32 v22, s[68:69], v20, v20, 1.0
	v_rcp_f32_e32 v24, v22
	v_pk_add_f32 v[18:19], v[18:19], 1.0 op_sel_hi:[1,0]
	v_fma_f32 v25, -v22, v24, 1.0
	v_fmac_f32_e32 v24, v25, v24
	v_div_scale_f32 v25, vcc, 1.0, v20, 1.0
	v_mul_f32_e32 v26, v25, v24
	v_fma_f32 v27, -v22, v26, v25
	v_fmac_f32_e32 v26, v27, v24
	v_fma_f32 v22, -v22, v26, v25
	v_div_fmas_f32 v22, v22, v24, v26
	v_div_fixup_f32 v20, v22, v20, 1.0
	v_div_scale_f32 v22, s[68:69], v19, v19, 1.0
	v_rcp_f32_e32 v24, v22
	s_nop 0
	v_fma_f32 v25, -v22, v24, 1.0
	v_fmac_f32_e32 v24, v25, v24
;   DI void operator()(const f32x16 (&acc)[4][2], bool vt, int row0, int col0, int r, int h, const float* sR, float* stage) const {
;     ...
;     else if (seg == 44) {
; #pragma unroll
;       for (int mi = 0; mi < 4; ++mi) {
;         const int row = row0 + mi * 32 + r;
;         const float rv = sR[mi * 32 + r];
; #pragma unroll
;         for (int g = 0; g < 3; ++g) {
;           f32x4 o;
; #pragma unroll
;           for (int q = 0; q < 4; ++q) o[q] = 1.f / (1.f + __expf(-acc[mi][0][4 * g + q] * rv));
;           *(f32x4*)(eb.gate + (size_t)row * 24 + 8 * g + 4 * h) = o;
;         }
;       }
	v_div_scale_f32 v25, vcc, 1.0, v19, 1.0
	v_mul_f32_e32 v26, v25, v24
	v_fma_f32 v27, -v22, v26, v25
	v_fmac_f32_e32 v26, v27, v24
	v_fma_f32 v22, -v22, v26, v25
	v_div_fmas_f32 v22, v22, v24, v26
	v_div_fixup_f32 v19, v22, v19, 1.0
	v_div_scale_f32 v22, s[68:69], v18, v18, 1.0
	v_rcp_f32_e32 v24, v22
	s_nop 0
	v_fma_f32 v25, -v22, v24, 1.0
	v_fmac_f32_e32 v24, v25, v24
	v_div_scale_f32 v25, vcc, 1.0, v18, 1.0
	v_mul_f32_e32 v26, v25, v24
	v_fma_f32 v27, -v22, v26, v25
	v_fmac_f32_e32 v26, v27, v24
	v_fma_f32 v22, -v22, v26, v25
	v_div_fmas_f32 v22, v22, v24, v26
	v_div_fixup_f32 v18, v22, v18, 1.0
	flat_store_dwordx4 v[14:15], v[18:21] offset:32
	s_nop 1
	v_mul_f32_e64 v20, v23, -v76
	v_mul_f32_e64 v21, v23, -v77
	v_mul_f32_e32 v20, 0x3fb8aa3b, v20
	v_mul_f32_e32 v21, 0x3fb8aa3b, v21
	v_exp_f32_e32 v20, v20
	v_exp_f32_e32 v21, v21
	v_mul_f32_e64 v18, v23, -v74
	v_mul_f32_e64 v19, v23, -v75
	v_mul_f32_e32 v18, 0x3fb8aa3b, v18
	v_pk_add_f32 v[20:21], v[20:21], 1.0 op_sel_hi:[1,0]
	v_mul_f32_e32 v19, 0x3fb8aa3b, v19
	v_div_scale_f32 v22, s[68:69], v21, v21, 1.0
	v_rcp_f32_e32 v23, v22
	v_exp_f32_e32 v18, v18
	v_exp_f32_e32 v19, v19
	v_fma_f32 v24, -v22, v23, 1.0
	v_fmac_f32_e32 v23, v24, v23
	v_div_scale_f32 v24, vcc, 1.0, v21, 1.0
	v_mul_f32_e32 v25, v24, v23
	v_fma_f32 v26, -v22, v25, v24
	v_fmac_f32_e32 v25, v26, v23
	v_fma_f32 v22, -v22, v25, v24
	v_div_fmas_f32 v22, v22, v23, v25
	v_div_fixup_f32 v21, v22, v21, 1.0
	v_div_scale_f32 v22, s[68:69], v20, v20, 1.0
	v_rcp_f32_e32 v23, v22
	v_pk_add_f32 v[18:19], v[18:19], 1.0 op_sel_hi:[1,0]
	v_fma_f32 v24, -v22, v23, 1.0
	v_fmac_f32_e32 v23, v24, v23
	v_div_scale_f32 v24, vcc, 1.0, v20, 1.0
	v_mul_f32_e32 v25, v24, v23
	v_fma_f32 v26, -v22, v25, v24
	v_fmac_f32_e32 v25, v26, v23
	v_fma_f32 v22, -v22, v25, v24
	v_div_fmas_f32 v22, v22, v23, v25
	v_div_fixup_f32 v20, v22, v20, 1.0
	v_div_scale_f32 v22, s[68:69], v19, v19, 1.0
	v_rcp_f32_e32 v23, v22
	s_nop 0
	v_fma_f32 v24, -v22, v23, 1.0
	v_fmac_f32_e32 v23, v24, v23
	v_div_scale_f32 v24, vcc, 1.0, v19, 1.0
	v_mul_f32_e32 v25, v24, v23
	v_fma_f32 v26, -v22, v25, v24
	v_fmac_f32_e32 v25, v26, v23
	v_fma_f32 v22, -v22, v25, v24
	v_div_fmas_f32 v22, v22, v23, v25
	v_div_fixup_f32 v19, v22, v19, 1.0
	v_div_scale_f32 v22, s[68:69], v18, v18, 1.0
	v_rcp_f32_e32 v23, v22
	s_nop 0
	v_fma_f32 v24, -v22, v23, 1.0
	v_fmac_f32_e32 v23, v24, v23
	v_div_scale_f32 v24, vcc, 1.0, v18, 1.0
	v_mul_f32_e32 v25, v24, v23
	v_fma_f32 v26, -v22, v25, v24
	v_fmac_f32_e32 v25, v26, v23
	v_fma_f32 v22, -v22, v25, v24
	v_div_fmas_f32 v22, v22, v23, v25
	v_div_fixup_f32 v18, v22, v18, 1.0
	flat_store_dwordx4 v[14:15], v[18:21] offset:64
	ds_read_b32 v23, v17 offset:256
	v_or_b32_e32 v22, 64, v16
	s_waitcnt lgkmcnt(0)
	v_mul_f32_e64 v18, v23, -v36
	v_mul_f32_e64 v19, v23, -v37
	v_mul_f32_e32 v18, 0x3fb8aa3b, v18
	v_mul_f32_e32 v19, 0x3fb8aa3b, v19
	v_exp_f32_e32 v18, v18
	v_exp_f32_e32 v19, v19
	v_mul_f32_e64 v14, v23, -v34
	v_mul_f32_e64 v15, v23, -v35
	v_mul_f32_e32 v14, 0x3fb8aa3b, v14
	v_pk_add_f32 v[18:19], v[18:19], 1.0 op_sel_hi:[1,0]
	v_mul_f32_e32 v15, 0x3fb8aa3b, v15
	v_div_scale_f32 v20, s[68:69], v19, v19, 1.0
	v_rcp_f32_e32 v21, v20
	v_exp_f32_e32 v14, v14
	v_exp_f32_e32 v15, v15
	v_fma_f32 v24, -v20, v21, 1.0
	v_fmac_f32_e32 v21, v24, v21
	v_div_scale_f32 v24, vcc, 1.0, v19, 1.0
	v_mul_f32_e32 v25, v24, v21
	v_fma_f32 v26, -v20, v25, v24
	v_fmac_f32_e32 v25, v26, v21
	v_fma_f32 v20, -v20, v25, v24
	v_div_fmas_f32 v20, v20, v21, v25
	v_div_fixup_f32 v21, v20, v19, 1.0
	v_div_scale_f32 v19, s[68:69], v18, v18, 1.0
	v_rcp_f32_e32 v20, v19
	v_pk_add_f32 v[14:15], v[14:15], 1.0 op_sel_hi:[1,0]
	v_fma_f32 v24, -v19, v20, 1.0
	v_fmac_f32_e32 v20, v24, v20
	v_div_scale_f32 v24, vcc, 1.0, v18, 1.0
	v_mul_f32_e32 v25, v24, v20
	v_fma_f32 v26, -v19, v25, v24
	v_fmac_f32_e32 v25, v26, v20
	v_fma_f32 v19, -v19, v25, v24
	v_div_fmas_f32 v19, v19, v20, v25
	v_div_fixup_f32 v20, v19, v18, 1.0
	v_div_scale_f32 v18, s[68:69], v15, v15, 1.0
	v_rcp_f32_e32 v19, v18
	s_nop 0
	v_fma_f32 v24, -v18, v19, 1.0
	v_fmac_f32_e32 v19, v24, v19
	v_div_scale_f32 v24, vcc, 1.0, v15, 1.0
	v_mul_f32_e32 v25, v24, v19
	v_fma_f32 v26, -v18, v25, v24
	v_fmac_f32_e32 v25, v26, v19
	v_fma_f32 v18, -v18, v25, v24
	v_div_fmas_f32 v18, v18, v19, v25
	v_div_fixup_f32 v19, v18, v15, 1.0
	v_div_scale_f32 v15, s[68:69], v14, v14, 1.0
	v_rcp_f32_e32 v18, v15
	s_nop 0
	v_fma_f32 v24, -v15, v18, 1.0
	v_fmac_f32_e32 v18, v24, v18
	v_div_scale_f32 v24, vcc, 1.0, v14, 1.0
	v_mul_f32_e32 v25, v24, v18
	v_fma_f32 v26, -v15, v25, v24
	v_fmac_f32_e32 v25, v26, v18
	v_fma_f32 v15, -v15, v25, v24
	v_div_fmas_f32 v15, v15, v18, v25
	v_div_fixup_f32 v18, v15, v14, 1.0
	v_mad_i64_i32 v[14:15], s[68:69], v22, s33, v[12:13]
	v_lshl_add_u64 v[14:15], v[14:15], 0, v[32:33]
	flat_store_dwordx4 v[14:15], v[18:21]
	s_nop 1
	v_mul_f32_e64 v20, v23, -v40
	v_mul_f32_e64 v21, v23, -v41
	v_mul_f32_e32 v20, 0x3fb8aa3b, v20
	v_mul_f32_e32 v21, 0x3fb8aa3b, v21
	v_exp_f32_e32 v20, v20
	v_exp_f32_e32 v21, v21
	v_mul_f32_e64 v18, v23, -v38
	v_mul_f32_e64 v19, v23, -v39
	v_mul_f32_e32 v18, 0x3fb8aa3b, v18
	v_pk_add_f32 v[20:21], v[20:21], 1.0 op_sel_hi:[1,0]
	v_mul_f32_e32 v19, 0x3fb8aa3b, v19
	v_div_scale_f32 v22, s[68:69], v21, v21, 1.0
	v_rcp_f32_e32 v24, v22
	v_exp_f32_e32 v18, v18
	v_exp_f32_e32 v19, v19
	v_fma_f32 v25, -v22, v24, 1.0
	v_fmac_f32_e32 v24, v25, v24
	v_div_scale_f32 v25, vcc, 1.0, v21, 1.0
	v_mul_f32_e32 v26, v25, v24
	v_fma_f32 v27, -v22, v26, v25
	v_fmac_f32_e32 v26, v27, v24
	v_fma_f32 v22, -v22, v26, v25
	v_div_fmas_f32 v22, v22, v24, v26
	v_div_fixup_f32 v21, v22, v21, 1.0
	v_div_scale_f32 v22, s[68:69], v20, v20, 1.0
;   DI void operator()(const f32x16 (&acc)[4][2], bool vt, int row0, int col0, int r, int h, const float* sR, float* stage) const {
;     ...
;     else if (seg == 44) {
; #pragma unroll
;       for (int mi = 0; mi < 4; ++mi) {
;         const int row = row0 + mi * 32 + r;
;         const float rv = sR[mi * 32 + r];
; #pragma unroll
;         for (int g = 0; g < 3; ++g) {
;           f32x4 o;
; #pragma unroll
;           for (int q = 0; q < 4; ++q) o[q] = 1.f / (1.f + __expf(-acc[mi][0][4 * g + q] * rv));
;           *(f32x4*)(eb.gate + (size_t)row * 24 + 8 * g + 4 * h) = o;
;         }
;       }
	v_rcp_f32_e32 v24, v22
	v_pk_add_f32 v[18:19], v[18:19], 1.0 op_sel_hi:[1,0]
	v_fma_f32 v25, -v22, v24, 1.0
	v_fmac_f32_e32 v24, v25, v24
	v_div_scale_f32 v25, vcc, 1.0, v20, 1.0
	v_mul_f32_e32 v26, v25, v24
	v_fma_f32 v27, -v22, v26, v25
	v_fmac_f32_e32 v26, v27, v24
	v_fma_f32 v22, -v22, v26, v25
	v_div_fmas_f32 v22, v22, v24, v26
	v_div_fixup_f32 v20, v22, v20, 1.0
	v_div_scale_f32 v22, s[68:69], v19, v19, 1.0
	v_rcp_f32_e32 v24, v22
	s_nop 0
	v_fma_f32 v25, -v22, v24, 1.0
	v_fmac_f32_e32 v24, v25, v24
	v_div_scale_f32 v25, vcc, 1.0, v19, 1.0
	v_mul_f32_e32 v26, v25, v24
	v_fma_f32 v27, -v22, v26, v25
	v_fmac_f32_e32 v26, v27, v24
	v_fma_f32 v22, -v22, v26, v25
	v_div_fmas_f32 v22, v22, v24, v26
	v_div_fixup_f32 v19, v22, v19, 1.0
	v_div_scale_f32 v22, s[68:69], v18, v18, 1.0
	v_rcp_f32_e32 v24, v22
	s_nop 0
	v_fma_f32 v25, -v22, v24, 1.0
	v_fmac_f32_e32 v24, v25, v24
	v_div_scale_f32 v25, vcc, 1.0, v18, 1.0
	v_mul_f32_e32 v26, v25, v24
	v_fma_f32 v27, -v22, v26, v25
	v_fmac_f32_e32 v26, v27, v24
	v_fma_f32 v22, -v22, v26, v25
	v_div_fmas_f32 v22, v22, v24, v26
	v_div_fixup_f32 v18, v22, v18, 1.0
	flat_store_dwordx4 v[14:15], v[18:21] offset:32
	s_nop 1
	v_mul_f32_e64 v20, v23, -v44
	v_mul_f32_e64 v21, v23, -v45
	v_mul_f32_e32 v20, 0x3fb8aa3b, v20
	v_mul_f32_e32 v21, 0x3fb8aa3b, v21
	v_exp_f32_e32 v20, v20
	v_exp_f32_e32 v21, v21
	v_mul_f32_e64 v18, v23, -v42
	v_mul_f32_e64 v19, v23, -v43
	v_mul_f32_e32 v18, 0x3fb8aa3b, v18
	v_pk_add_f32 v[20:21], v[20:21], 1.0 op_sel_hi:[1,0]
	v_mul_f32_e32 v19, 0x3fb8aa3b, v19
	v_div_scale_f32 v22, s[68:69], v21, v21, 1.0
	v_rcp_f32_e32 v23, v22
	v_exp_f32_e32 v18, v18
	v_exp_f32_e32 v19, v19
	v_fma_f32 v24, -v22, v23, 1.0
	v_fmac_f32_e32 v23, v24, v23
	v_div_scale_f32 v24, vcc, 1.0, v21, 1.0
	v_mul_f32_e32 v25, v24, v23
	v_fma_f32 v26, -v22, v25, v24
	v_fmac_f32_e32 v25, v26, v23
	v_fma_f32 v22, -v22, v25, v24
	v_div_fmas_f32 v22, v22, v23, v25
	v_div_fixup_f32 v21, v22, v21, 1.0
	v_div_scale_f32 v22, s[68:69], v20, v20, 1.0
	v_rcp_f32_e32 v23, v22
	v_pk_add_f32 v[18:19], v[18:19], 1.0 op_sel_hi:[1,0]
	v_fma_f32 v24, -v22, v23, 1.0
	v_fmac_f32_e32 v23, v24, v23
	v_div_scale_f32 v24, vcc, 1.0, v20, 1.0
	v_mul_f32_e32 v25, v24, v23
	v_fma_f32 v26, -v22, v25, v24
	v_fmac_f32_e32 v25, v26, v23
	v_fma_f32 v22, -v22, v25, v24
	v_div_fmas_f32 v22, v22, v23, v25
	v_div_fixup_f32 v20, v22, v20, 1.0
	v_div_scale_f32 v22, s[68:69], v19, v19, 1.0
	v_rcp_f32_e32 v23, v22
	s_nop 0
	v_fma_f32 v24, -v22, v23, 1.0
	v_fmac_f32_e32 v23, v24, v23
	v_div_scale_f32 v24, vcc, 1.0, v19, 1.0
	v_mul_f32_e32 v25, v24, v23
	v_fma_f32 v26, -v22, v25, v24
	v_fmac_f32_e32 v25, v26, v23
	v_fma_f32 v22, -v22, v25, v24
	v_div_fmas_f32 v22, v22, v23, v25
	v_div_fixup_f32 v19, v22, v19, 1.0
	v_div_scale_f32 v22, s[68:69], v18, v18, 1.0
	v_rcp_f32_e32 v23, v22
	s_nop 0
	v_fma_f32 v24, -v22, v23, 1.0
	v_fmac_f32_e32 v23, v24, v23
	v_div_scale_f32 v24, vcc, 1.0, v18, 1.0
	v_mul_f32_e32 v25, v24, v23
	v_fma_f32 v26, -v22, v25, v24
	v_fmac_f32_e32 v25, v26, v23
	v_fma_f32 v22, -v22, v25, v24
	v_div_fmas_f32 v22, v22, v23, v25
	v_div_fixup_f32 v18, v22, v18, 1.0
	flat_store_dwordx4 v[14:15], v[18:21] offset:64
	ds_read_b32 v19, v17 offset:384
	s_waitcnt lgkmcnt(0)
;   DI void operator()(const f32x16 (&acc)[4][2], bool vt, int row0, int col0, int r, int h, const float* sR, float* stage) const {
;     ...
;     else if (seg == 44) {
; #pragma unroll
;       for (int mi = 0; mi < 4; ++mi) {
;         const int row = row0 + mi * 32 + r;
;         const float rv = sR[mi * 32 + r];
; #pragma unroll
;         for (int g = 0; g < 3; ++g) {
;           f32x4 o;
; #pragma unroll
;           for (int q = 0; q < 4; ++q) o[q] = 1.f / (1.f + __expf(-acc[mi][0][4 * g + q] * rv));
;           *(f32x4*)(eb.gate + (size_t)row * 24 + 8 * g + 4 * h) = o;
;         }
;       }
	v_mul_f32_e64 v2, v19, -v2
	v_mul_f32_e64 v3, v19, -v3
	v_mul_f32_e32 v2, 0x3fb8aa3b, v2
	v_mul_f32_e32 v3, 0x3fb8aa3b, v3
	v_exp_f32_e32 v2, v2
	v_exp_f32_e32 v3, v3
	v_or_b32_e32 v18, 0x60, v16
	v_mul_f32_e64 v0, v19, -v0
	v_mul_f32_e64 v1, v19, -v1
	v_pk_add_f32 v[2:3], v[2:3], 1.0 op_sel_hi:[1,0]
	v_mul_f32_e32 v0, 0x3fb8aa3b, v0
	v_div_scale_f32 v14, s[68:69], v3, v3, 1.0
	v_rcp_f32_e32 v15, v14
	v_mul_f32_e32 v1, 0x3fb8aa3b, v1
	v_exp_f32_e32 v0, v0
	v_exp_f32_e32 v1, v1
	v_fma_f32 v16, -v14, v15, 1.0
	v_fmac_f32_e32 v15, v16, v15
	v_div_scale_f32 v16, vcc, 1.0, v3, 1.0
	v_mul_f32_e32 v17, v16, v15
	v_fma_f32 v20, -v14, v17, v16
	v_fmac_f32_e32 v17, v20, v15
	v_fma_f32 v14, -v14, v17, v16
	v_div_fmas_f32 v14, v14, v15, v17
	v_div_fixup_f32 v17, v14, v3, 1.0
	v_div_scale_f32 v3, s[68:69], v2, v2, 1.0
	v_rcp_f32_e32 v14, v3
	v_pk_add_f32 v[0:1], v[0:1], 1.0 op_sel_hi:[1,0]
	v_fma_f32 v15, -v3, v14, 1.0
	v_fmac_f32_e32 v14, v15, v14
	v_div_scale_f32 v15, vcc, 1.0, v2, 1.0
	v_mul_f32_e32 v16, v15, v14
	v_fma_f32 v20, -v3, v16, v15
	v_fmac_f32_e32 v16, v20, v14
	v_fma_f32 v3, -v3, v16, v15
	v_div_fmas_f32 v3, v3, v14, v16
	v_div_fixup_f32 v16, v3, v2, 1.0
	v_div_scale_f32 v2, s[68:69], v1, v1, 1.0
	v_rcp_f32_e32 v3, v2
	s_nop 0
	v_fma_f32 v14, -v2, v3, 1.0
	v_fmac_f32_e32 v3, v14, v3
	v_div_scale_f32 v14, vcc, 1.0, v1, 1.0
	v_mul_f32_e32 v15, v14, v3
	v_fma_f32 v20, -v2, v15, v14
	v_fmac_f32_e32 v15, v20, v3
	v_fma_f32 v2, -v2, v15, v14
	v_div_fmas_f32 v2, v2, v3, v15
	v_div_fixup_f32 v15, v2, v1, 1.0
	v_div_scale_f32 v1, s[68:69], v0, v0, 1.0
	v_rcp_f32_e32 v2, v1
	s_nop 0
	v_fma_f32 v3, -v1, v2, 1.0
	v_fmac_f32_e32 v2, v3, v2
	v_div_scale_f32 v3, vcc, 1.0, v0, 1.0
	v_mul_f32_e32 v14, v3, v2
	v_fma_f32 v20, -v1, v14, v3
	v_fmac_f32_e32 v14, v20, v2
	v_fma_f32 v1, -v1, v14, v3
	v_div_fmas_f32 v1, v1, v2, v14
	v_mul_f32_e64 v2, v19, -v4
	v_mul_f32_e64 v3, v19, -v5
	v_mul_f32_e64 v4, v19, -v6
	v_mul_f32_e64 v5, v19, -v7
	v_mul_f32_e32 v4, 0x3fb8aa3b, v4
	v_mul_f32_e32 v5, 0x3fb8aa3b, v5
	v_exp_f32_e32 v4, v4
	v_exp_f32_e32 v5, v5
	v_div_fixup_f32 v14, v1, v0, 1.0
	v_mad_i64_i32 v[0:1], s[68:69], v18, s33, v[12:13]
	v_pk_add_f32 v[4:5], v[4:5], 1.0 op_sel_hi:[1,0]
	v_lshl_add_u64 v[0:1], v[0:1], 0, v[32:33]
	v_div_scale_f32 v6, s[68:69], v5, v5, 1.0
	v_rcp_f32_e32 v7, v6
	flat_store_dwordx4 v[0:1], v[14:17]
	v_mul_f32_e32 v2, 0x3fb8aa3b, v2
	v_mul_f32_e32 v3, 0x3fb8aa3b, v3
	v_fma_f32 v12, -v6, v7, 1.0
	v_fmac_f32_e32 v7, v12, v7
	v_div_scale_f32 v12, vcc, 1.0, v5, 1.0
	v_mul_f32_e32 v13, v12, v7
	v_fma_f32 v14, -v6, v13, v12
	v_fmac_f32_e32 v13, v14, v7
	v_fma_f32 v6, -v6, v13, v12
	v_div_fmas_f32 v6, v6, v7, v13
	v_div_fixup_f32 v5, v6, v5, 1.0
	v_div_scale_f32 v6, s[68:69], v4, v4, 1.0
	v_rcp_f32_e32 v7, v6
	v_exp_f32_e32 v2, v2
	v_exp_f32_e32 v3, v3
	v_fma_f32 v12, -v6, v7, 1.0
	v_fmac_f32_e32 v7, v12, v7
	v_div_scale_f32 v12, vcc, 1.0, v4, 1.0
	v_mul_f32_e32 v13, v12, v7
	v_fma_f32 v14, -v6, v13, v12
	v_fmac_f32_e32 v13, v14, v7
	v_fma_f32 v6, -v6, v13, v12
	v_pk_add_f32 v[2:3], v[2:3], 1.0 op_sel_hi:[1,0]
	v_div_fmas_f32 v6, v6, v7, v13
	v_div_fixup_f32 v4, v6, v4, 1.0
	v_div_scale_f32 v6, s[68:69], v3, v3, 1.0
	v_rcp_f32_e32 v7, v6
	s_nop 0
	v_fma_f32 v12, -v6, v7, 1.0
	v_fmac_f32_e32 v7, v12, v7
	v_div_scale_f32 v12, vcc, 1.0, v3, 1.0
	v_mul_f32_e32 v13, v12, v7
	v_fma_f32 v14, -v6, v13, v12
	v_fmac_f32_e32 v13, v14, v7
	v_fma_f32 v6, -v6, v13, v12
	v_div_fmas_f32 v6, v6, v7, v13
	v_div_fixup_f32 v3, v6, v3, 1.0
	v_div_scale_f32 v6, s[68:69], v2, v2, 1.0
	v_rcp_f32_e32 v7, v6
	s_nop 0
	v_fma_f32 v12, -v6, v7, 1.0
	v_fmac_f32_e32 v7, v12, v7
	v_div_scale_f32 v12, vcc, 1.0, v2, 1.0
	v_mul_f32_e32 v13, v12, v7
	v_fma_f32 v14, -v6, v13, v12
	v_fmac_f32_e32 v13, v14, v7
	v_fma_f32 v6, -v6, v13, v12
	v_div_fmas_f32 v6, v6, v7, v13
	v_div_fixup_f32 v2, v6, v2, 1.0
	flat_store_dwordx4 v[0:1], v[2:5] offset:32
	s_nop 1
	v_mul_f32_e64 v4, v19, -v10
	v_mul_f32_e64 v5, v19, -v11
	v_mul_f32_e32 v4, 0x3fb8aa3b, v4
	v_mul_f32_e32 v5, 0x3fb8aa3b, v5
	v_exp_f32_e32 v4, v4
	v_exp_f32_e32 v5, v5
	v_mul_f32_e64 v2, v19, -v8
	v_mul_f32_e64 v3, v19, -v9
	v_mul_f32_e32 v2, 0x3fb8aa3b, v2
	v_pk_add_f32 v[4:5], v[4:5], 1.0 op_sel_hi:[1,0]
	v_mul_f32_e32 v3, 0x3fb8aa3b, v3
	v_div_scale_f32 v6, s[68:69], v5, v5, 1.0
	v_rcp_f32_e32 v7, v6
	v_exp_f32_e32 v2, v2
	v_exp_f32_e32 v3, v3
	v_fma_f32 v8, -v6, v7, 1.0
	v_fmac_f32_e32 v7, v8, v7
	v_div_scale_f32 v8, vcc, 1.0, v5, 1.0
	v_mul_f32_e32 v9, v8, v7
	v_fma_f32 v10, -v6, v9, v8
	v_fmac_f32_e32 v9, v10, v7
	v_fma_f32 v6, -v6, v9, v8
	v_div_fmas_f32 v6, v6, v7, v9
	v_div_fixup_f32 v5, v6, v5, 1.0
	v_div_scale_f32 v6, s[68:69], v4, v4, 1.0
	v_rcp_f32_e32 v7, v6
	v_pk_add_f32 v[2:3], v[2:3], 1.0 op_sel_hi:[1,0]
	v_fma_f32 v8, -v6, v7, 1.0
	v_fmac_f32_e32 v7, v8, v7
	v_div_scale_f32 v8, vcc, 1.0, v4, 1.0
	v_mul_f32_e32 v9, v8, v7
	v_fma_f32 v10, -v6, v9, v8
	v_fmac_f32_e32 v9, v10, v7
	v_fma_f32 v6, -v6, v9, v8
	v_div_fmas_f32 v6, v6, v7, v9
	v_div_fixup_f32 v4, v6, v4, 1.0
	v_div_scale_f32 v6, s[68:69], v3, v3, 1.0
	v_rcp_f32_e32 v7, v6
	s_nop 0
	v_fma_f32 v8, -v6, v7, 1.0
	v_fmac_f32_e32 v7, v8, v7
	v_div_scale_f32 v8, vcc, 1.0, v3, 1.0
	v_mul_f32_e32 v9, v8, v7
	v_fma_f32 v10, -v6, v9, v8
	v_fmac_f32_e32 v9, v10, v7
	v_fma_f32 v6, -v6, v9, v8
	v_div_fmas_f32 v6, v6, v7, v9
	v_div_fixup_f32 v3, v6, v3, 1.0
	v_div_scale_f32 v6, s[68:69], v2, v2, 1.0
	v_rcp_f32_e32 v7, v6
	s_nop 0
	v_fma_f32 v8, -v6, v7, 1.0
	v_fmac_f32_e32 v7, v8, v7
	v_div_scale_f32 v8, vcc, 1.0, v2, 1.0
	v_mul_f32_e32 v9, v8, v7
	v_fma_f32 v10, -v6, v9, v8
	v_fmac_f32_e32 v9, v10, v7
	v_fma_f32 v6, -v6, v9, v8
	v_div_fmas_f32 v6, v6, v7, v9
	v_div_fixup_f32 v2, v6, v2, 1.0
	flat_store_dwordx4 v[0:1], v[2:5] offset:64
